# P1 prologue: gate-weight fragments of w_in loaded once per workgroup (4 loads per wave) and shared through LDS instead of 32 scattered loads in each of the 8 waves
# speedup vs baseline: 1.0046x; 1.0013x over previous
; DI void phase1(const Params& p, unsigned char* smem) {
;     ...
;     float4 gw0[16], gw1[16];
; #pragma unroll
;     for (int i = 0; i < 4; ++i)
; #pragma unroll
;         for (int e = 0; e < 4; ++e) {
;             const float* wp = p.in[4] + (size_t)(i * 256 + lane * 4 + e) * 4616 + 2048;
;             gw0[i * 4 + e] = *(const float4*)wp; gw1[i * 4 + e] = *(const float4*)(wp + 4);
;         }
.LBB0_184:
	s_or_b64 exec, exec, s[0:1]
	s_add_u32 s62, s70, 0x2000000
	s_addc_u32 s63, s71, 0
	s_add_u32 s94, s70, 0x4000000
	s_addc_u32 s95, s71, 0
	s_add_u32 s88, s70, 0x325c000
	v_mov_b32_e32 v0, v250
	s_addc_u32 s89, s71, 0
	s_waitcnt lgkmcnt(0)
	s_barrier
	v_lshlrev_b32_e32 v150, 4, v250
	v_add_u32_e32 v151, 0x6000, v150
	v_add_u32_e32 v152, 0xc000, v150
	v_add_u32_e32 v153, 0x12000, v150
	global_load_dwordx4 v[156:159], v150, s[62:63]
	global_load_dwordx4 v[160:163], v151, s[62:63]
	global_load_dwordx4 v[164:167], v152, s[62:63]
	global_load_dwordx4 v[168:171], v153, s[62:63]
	s_waitcnt vmcnt(3)
	ds_write_b128 v150, v[156:159] offset:1024
	s_waitcnt vmcnt(2)
	ds_write_b128 v150, v[160:163] offset:9216
	s_waitcnt vmcnt(1)
	ds_write_b128 v150, v[164:167] offset:17408
	s_waitcnt vmcnt(0)
	ds_write_b128 v150, v[168:171] offset:25600
	s_waitcnt lgkmcnt(0)
	s_barrier
	s_add_u32 s20, s70, 0x32dc000
	v_ashrrev_i32_e32 v1, 4, v0
	s_addc_u32 s21, s71, 0
	s_lshl_b32 s0, s2, 5
	v_and_b32_e32 v1, -4, v1
	v_writelane_b32 v254, s0, 52
	v_add_u32_e32 v176, s0, v1
	s_mov_b32 s0, 0x8000
	v_cmp_gt_i32_e32 vcc, s0, v176
	s_and_saveexec_b64 s[22:23], vcc
	s_cbranch_execz .LBB0_219
	v_and_b32_e32 v230, 63, v0
	v_readfirstlane_b32 s4, v0
	v_readlane_b32 s36, v254, 4
	v_mov_b32_e32 v179, 0
	v_readlane_b32 s44, v254, 12
	v_readlane_b32 s45, v254, 13
	s_lshr_b32 s4, s4, 6
	s_lshr_b32 s5, s4, 1
	s_and_b32 s6, s4, 1
	s_mul_i32 s5, s5, 0x482000
	s_mul_i32 s6, s6, 0x9040
	s_add_i32 s5, s5, s6
	s_add_i32 s5, s5, 0x2000
	s_add_u32 s8, s44, s5
	s_addc_u32 s9, s45, 0
	s_add_u32 s10, s8, 0x4820
	s_addc_u32 s11, s9, 0
	v_mul_u32_u24_e32 v168, 0x12080, v230
	v_lshlrev_b32_e32 v128, 2, v230
	v_or_b32_e32 v130, 0x100, v128
	s_mov_b64 s[16:17], 0x2000
	global_load_dwordx4 v[152:155], v168, s[8:9]
	global_load_dwordx4 v[156:159], v168, s[8:9] offset:16
	global_load_dwordx4 v[160:163], v168, s[10:11]
	global_load_dwordx4 v[164:167], v168, s[10:11] offset:16
	v_lshlrev_b32_e32 v170, 4, v230
	s_lshl_b32 s6, s4, 12
	v_add_u32_e32 v169, s6, v170
	v_add_u32_e32 v170, 0x8800, v170
	s_waitcnt vmcnt(3)
	ds_write_b128 v169, v[152:155] offset:34816
	s_waitcnt vmcnt(2)
	ds_write_b128 v169, v[156:159] offset:35840
	s_waitcnt vmcnt(1)
	ds_write_b128 v169, v[160:163] offset:36864
	s_waitcnt vmcnt(0)
	ds_write_b128 v169, v[164:167] offset:37888
	s_waitcnt lgkmcnt(0)
	s_barrier
	ds_read_b128 v[0:3], v170
	ds_read_b128 v[4:7], v170 offset:1024
	ds_read_b128 v[8:11], v170 offset:2048
	ds_read_b128 v[12:15], v170 offset:3072
	ds_read_b128 v[16:19], v170 offset:4096
	ds_read_b128 v[20:23], v170 offset:5120
	ds_read_b128 v[24:27], v170 offset:6144
	ds_read_b128 v[28:31], v170 offset:7168
	ds_read_b128 v[32:35], v170 offset:8192
	ds_read_b128 v[36:39], v170 offset:9216
	ds_read_b128 v[40:43], v170 offset:10240
	ds_read_b128 v[44:47], v170 offset:11264
	ds_read_b128 v[48:51], v170 offset:12288
	ds_read_b128 v[52:55], v170 offset:13312
	ds_read_b128 v[56:59], v170 offset:14336
	ds_read_b128 v[60:63], v170 offset:15360
	ds_read_b128 v[64:67], v170 offset:16384
	ds_read_b128 v[68:71], v170 offset:17408
	ds_read_b128 v[72:75], v170 offset:18432
	ds_read_b128 v[76:79], v170 offset:19456
	ds_read_b128 v[80:83], v170 offset:20480
	ds_read_b128 v[84:87], v170 offset:21504
	ds_read_b128 v[88:91], v170 offset:22528
	ds_read_b128 v[92:95], v170 offset:23552
	ds_read_b128 v[96:99], v170 offset:24576
	ds_read_b128 v[100:103], v170 offset:25600
	ds_read_b128 v[104:107], v170 offset:26624
	ds_read_b128 v[108:111], v170 offset:27648
	ds_read_b128 v[112:115], v170 offset:28672
	ds_read_b128 v[116:119], v170 offset:29696
	ds_read_b128 v[120:123], v170 offset:30720
	ds_read_b128 v[124:127], v170 offset:31744
	s_waitcnt lgkmcnt(0)
	v_readlane_b32 s37, v254, 5
	v_readlane_b32 s46, v254, 14
	v_readlane_b32 s47, v254, 15
	v_mov_b32_e32 v129, v179
	v_lshlrev_b32_e32 v178, 4, v230
	v_readlane_b32 s38, v254, 6
	v_readlane_b32 s39, v254, 7
	v_readlane_b32 s40, v254, 8
	v_or_b32_e32 v132, 0x200, v128
	v_or_b32_e32 v134, 0x300, v128
	v_subrev_co_u32_e64 v231, s[0:1], 4, v230
	v_lshl_add_u64 v[180:181], s[36:37], 0, v[178:179]
	v_lshl_add_u64 v[136:137], s[46:47], 0, v[128:129]
	v_lshlrev_b32_e32 v178, 3, v230
	v_cmp_gt_u32_e32 vcc, 8, v230
	s_xor_b64 s[24:25], s[0:1], -1
	s_lshl_b32 s3, s33, 5
	v_cmp_eq_u32_e64 s[0:1], 1, v230
	v_cmp_eq_u32_e64 s[14:15], 2, v230
	v_cmp_eq_u32_e64 s[4:5], 3, v230
	v_cmp_eq_u32_e64 s[6:7], 4, v230
	v_cmp_eq_u32_e64 s[8:9], 5, v230
	v_cmp_eq_u32_e64 s[10:11], 6, v230
	v_cmp_eq_u32_e64 s[12:13], 7, v230
	v_lshl_add_u64 v[182:183], v[136:137], 0, s[16:17]
	v_lshl_add_u64 v[184:185], s[94:95], 0, v[178:179]
	s_mov_b64 s[26:27], 0
	v_lshlrev_b32_e32 v178, 2, v128
	v_lshlrev_b32_e32 v186, 2, v130
	v_lshlrev_b32_e32 v188, 2, v132
	v_lshlrev_b32_e32 v190, 2, v134
	v_mov_b32_e32 v232, 0x3727c5ac
	s_mov_b32 s36, 0x800000
	s_mov_b32 s37, 0x3f2aaaab
	v_mov_b32_e32 v233, 0x3ecc95a3
	s_mov_b32 s38, 0x3f317218
	s_mov_b32 s39, 0x7f800000
	s_mov_b32 s40, 0x33800000
	v_mov_b32_e32 v234, 0x7f800000
	v_mov_b32_e32 v235, 0x7fc00000
	v_mov_b32_e32 v236, 0xff800000
	v_mov_b32_e32 v192, 0x3f317218
	v_readlane_b32 s41, v254, 9
	v_readlane_b32 s42, v254, 10
	v_readlane_b32 s43, v254, 11
	v_readlane_b32 s48, v254, 16
	v_readlane_b32 s49, v254, 17
	v_readlane_b32 s50, v254, 18
	v_readlane_b32 s51, v254, 19
	global_load_dword v251, v[182:183], off
	s_branch .LBB0_189
